# in-proj and gate-up phases: 4-group staggered start (~1.6us steps); on top of v6
# baseline (speedup 1.0000x reference)
; #define PG8_STAGE(bufoff, gbase, voff) do { _Pragma("unroll") for (int _i = 0; _i < 2; ++_i) \
;         __builtin_amdgcn_global_load_lds((const unsigned*)((const char*)(gbase) + (voff)[_i]), (PG8_LAS unsigned*)(lds + (bufoff) + ldsw + _i * 8192), 16, 0, 0); } while (0)
; #define PG8_WAIT_V(n) asm volatile("s_waitcnt vmcnt(" #n ")" ::: "memory")
; #define PG8_BAR __builtin_amdgcn_s_barrier()
; template <class Epi, class Sched, bool ALIGN_EPI = false, bool SP2 = false>
; __device__ __forceinline__ void gemm_phase(PG8_LAS unsigned char* lds, const Gemm g, const Sched& S, const Epi& E) {
;     ...
;     if constexpr (SP2) {
;         PG8_STAGE(PG8_SB(0, 0), cB, voffB); PG8_STAGE(PG8_SB(0, 1), cB + hstep, voffB); PG8_STAGE(PG8_SA(0, 0), cA, voffA); PG8_STAGE(PG8_SA(0, 1), cA + hstep, voffA);
;         if (wr == 1) PG8_BAR;
;         PG8_WAIT_V(2); PG8_BAR;
;         PG8_STAGE(PG8_SB(1, 0), cB + kstep, voffB); PG8_STAGE(PG8_SA(1, 0), cA + kstep, voffA); PG8_STAGE(PG8_SB(1, 1), cB + hstep + kstep, voffB);
;         PG8_WAIT_V(6); PG8_BAR;
.LBB0_401:
	v_readlane_b32 s1, v255, 25
	s_lshl_b32 s38, s1, 6
	s_and_b32 s1, s2, 3
	s_lshl_b32 s2, s20, 6
	s_add_i32 m0, s92, 0x18000
	v_lshl_add_u64 v[8:9], v[8:9], 0, s[26:27]
	s_ashr_i32 s39, s38, 31
	v_writelane_b32 v255, s2, 25
	s_lshl_b32 s21, s20, 13
	s_lshl_b32 s24, s1, 5
	s_lshl_b32 s30, s1, 12
	s_waitcnt vmcnt(2)
	s_barrier
	global_load_lds_dwordx4 v[8:9], off
	v_lshl_add_u64 v[6:7], v[6:7], 0, s[26:27]
	s_add_i32 m0, s92, 0x1a000
	s_add_i32 s20, s92, 0x8000
	s_add_i32 s2, s92, 0xa000
	global_load_lds_dwordx4 v[6:7], off
	v_lshl_add_u64 v[2:3], v[2:3], 0, s[26:27]
	s_mov_b32 m0, s20
	s_add_u32 s42, s36, 0x40080
	global_load_lds_dwordx4 v[2:3], off
	v_lshl_add_u64 v[2:3], v[4:5], 0, s[26:27]
	s_mov_b32 m0, s2
	s_addc_u32 s43, s37, 0
	global_load_lds_dwordx4 v[2:3], off
	s_add_i32 m0, s92, 0x1c000
	v_lshl_add_u64 v[2:3], s[42:43], 0, v[162:163]
	global_load_lds_dwordx4 v[2:3], off
	v_lshl_add_u64 v[2:3], s[42:43], 0, v[164:165]
	s_add_i32 m0, s92, 0x1e000
	v_bfe_u32 v199, v0, 4, 2
	global_load_lds_dwordx4 v[2:3], off
	v_and_b32_e32 v198, 15, v0
	v_lshlrev_b32_e32 v2, 4, v199
	v_lshlrev_b32_e32 v0, 2, v0
	v_lshl_or_b32 v2, v198, 6, v2
	v_and_b32_e32 v0, 32, v0
	s_cmpk_lt_u32 s23, 0x100
	v_bitop3_b32 v200, v2, s30, v0 bitop3:0xde
	s_cselect_b64 s[30:31], -1, 0
	v_writelane_b32 v255, s30, 37
	v_bitop3_b32 v3, v2, s21, v0 bitop3:0xde
	s_lshl_b32 s21, s1, 6
	v_writelane_b32 v255, s31, 38
	v_writelane_b32 v255, s21, 39
	s_or_b32 s21, s21, 0xfffff900
	s_cmp_gt_u32 s1, 1
	v_writelane_b32 v255, s21, 40
	s_cselect_b64 s[30:31], -1, 0
	v_writelane_b32 v255, s30, 41
	v_lshlrev_b32_e32 v0, 14, v10
	v_and_b32_e32 v0, 0xffff8000, v0
	v_writelane_b32 v255, s31, 42
	s_mov_b32 s30, s44
	v_readlane_b32 s1, v255, 28
	s_ashr_i32 s1, s1, 31
	s_mov_b32 s31, s25
	v_writelane_b32 v255, s1, 43
	s_or_b32 s1, s24, 0xfffffb80
	v_writelane_b32 v255, s1, 44
	v_writelane_b32 v255, s30, 45
	s_lshr_b32 s1, s30, 3
	s_mov_b32 s51, 0
	v_writelane_b32 v255, s31, 46
	v_writelane_b32 v255, s1, 47
	v_lshl_add_u32 v0, v11, 11, v0
	v_readlane_b32 s30, v255, 21
	v_readlane_b32 s31, v255, 22
	s_and_b64 s[42:43], s[30:31], exec
	s_cselect_b32 s1, 15, 16
	v_writelane_b32 v255, s1, 48
	s_mov_b32 s1, 0x60000
	s_cselect_b32 s50, 0x30000, s1
	s_mov_b32 s1, 0xc0000
	v_and_b32_e32 v2, 1, v10
	s_cselect_b32 s30, s1, 0x180000
	s_mov_b32 s31, s51
	v_lshl_or_b32 v0, v2, 6, v0
	v_writelane_b32 v255, s30, 49
	s_add_i32 s47, s60, -1
	s_lshl_b32 s54, s58, 1
	s_lshl_b32 s56, s58, 2
	s_mov_b32 s1, s58
	s_lshl_b32 s58, s58, 3
	v_lshl_add_u32 v166, v12, 1, v0
	v_lshlrev_b32_e32 v0, 14, v13
	v_writelane_b32 v255, s31, 50
	s_sub_u32 s62, 0, s54
	v_and_b32_e32 v0, 0xffff8000, v0
	s_waitcnt vmcnt(6)
	v_writelane_b32 v255, s60, 51
	s_subb_u32 s63, 0, 0
	v_lshl_add_u32 v0, v14, 11, v0
	v_and_b32_e32 v2, 1, v13
	s_lshl_b64 s[30:31], s[38:39], 2
	v_lshl_or_b32 v0, v2, 6, v0
	v_writelane_b32 v255, s30, 52
	s_mov_b32 s55, s25
	s_mov_b32 s57, s25
	s_mov_b32 s59, s25
	s_mul_hi_i32 s61, s1, -14
	s_mul_i32 s60, s1, -14
	v_mov_b32_e32 v167, v1
	v_lshl_add_u32 v168, v15, 1, v0
	v_mov_b32_e32 v169, v1
	s_lshl_b32 s24, s1, 1
	v_writelane_b32 v255, s31, 53
	v_add_u32_e32 v201, 0, v3
	s_mov_b32 s46, s51
	s_barrier
	v_readlane_b32 s66, v253, 0
	s_nop 3
	s_and_b32 s66, s66, 3
	s_cbranch_scc0 .Lip_stag_done
.Lip_stag:
	s_sleep 50
	s_add_i32 s66, s66, -1
	s_cmp_lg_u32 s66, 0
	s_cbranch_scc1 .Lip_stag
